# static s_setprio 1 for waves 4-7 during each diff-attention pass
# baseline (speedup 1.0000x reference)
; DI int tid() { int t = __builtin_amdgcn_workitem_id_x(); asm volatile("" : "+v"(t)); return t; }
; DI f32x16 zero16() { f32x16 z; for (int i = 0; i < 16; ++i) z[i] = 0.f; return z; }
; DI f32x16 splat16(float v) { f32x16 z; for (int i = 0; i < 16; ++i) z[i] = v; return z; }
; DI void diff_pass(const bf16_t* __restrict__ qrow  , const bf16_t* __restrict__ kg, const bf16_t* __restrict__ vg,
;                   int nkt, int q0, float negM2, f32x16 (&O)[4], float& lsum, char* lds) {
;     const int t = tid(), lane = t & 63, wv = t >> 6, h = lane >> 5, l31 = lane & 31, f = (lane >> 1) & 7;
;     const int lr = t >> 3, lc = t & 7;
;     const int sc = (lc ^ ((lr >> 1) & 7)) - lc;
;     const bf16_t* kgs = kg + sc * 8;
;     const bf16_t* vgs = vg + sc * 8;
;     const int wb = wv * 1024;
;     const int qpos = q0 + l31;
;     bf16x8 qf[4];
; #pragma unroll
;     for (int ks = 0; ks < 4; ++ks) qf[ks] = *(const bf16x8*)(qrow + 16 * ks + 8 * h);
; #pragma unroll
;     for (int d = 0; d < 4; ++d) O[d] = zero16();
;     lsum = 0.f;
;     const f32x16 minit = splat16(negM2);
;     __syncthreads();
;     __builtin_amdgcn_global_load_lds((const unsigned*)kgs, (lds_ptr_t)(lds + wb), 16, 0, 0);
;     __builtin_amdgcn_global_load_lds((const unsigned*)vgs, (lds_ptr_t)(lds + 8192 + wb), 16, 0, 0);
;     __builtin_amdgcn_global_load_lds((const unsigned*)(vgs + (size_t)64 * kS), (lds_ptr_t)(lds + 16384 + wb), 16, 0, 0);
;     asm volatile("s_waitcnt vmcnt(0)" ::: "memory");
;     __syncthreads();
.LBB0_85:
	v_mov_b32_e32 v8, v162
	v_cmp_lt_u32_e32 vcc, 0xff, v162
	s_cbranch_vccz .Lnp1
	s_setprio 1
.Lnp1:
	s_lshl_b64 s[28:29], s[28:29], 1
	v_lshrrev_b32_e32 v6, 4, v8
	v_and_b32_e32 v0, 7, v8
	v_bitop3_b32 v6, v6, 7, v8 bitop3:0x48
	v_sub_u32_e32 v0, v6, v0
	v_bfe_u32 v9, v8, 5, 1
	v_lshlrev_b32_e32 v6, 3, v0
	v_lshlrev_b32_e32 v0, 4, v8
	v_lshl_add_u64 v[4:5], v[144:145], 0, s[28:29]
	v_ashrrev_i32_e32 v7, 31, v6
	v_and_b32_e32 v187, 0xfffffc00, v0
	v_lshlrev_b32_e32 v0, 4, v9
	v_lshl_add_u64 v[2:3], v[152:153], 0, s[28:29]
	v_lshlrev_b64 v[158:159], 1, v[6:7]
	v_lshl_add_u64 v[4:5], v[4:5], 0, v[0:1]
	v_readfirstlane_b32 s30, v187
	v_add_u32_e32 v0, 0x2000, v187
	v_lshl_add_u64 v[2:3], v[2:3], 0, v[158:159]
	global_load_dwordx4 v[140:143], v[4:5], off
	global_load_dwordx4 v[136:139], v[4:5], off offset:32
	global_load_dwordx4 v[132:135], v[4:5], off offset:64
	global_load_dwordx4 v[128:131], v[4:5], off offset:96
	s_mov_b32 m0, s30
	v_readfirstlane_b32 s30, v0
	v_add_u32_e32 v0, 0x4000, v187
	v_lshl_add_u64 v[4:5], v[150:151], 0, v[158:159]
	s_barrier
	global_load_lds_dwordx4 v[2:3], off
	s_mov_b32 m0, s30
	v_readfirstlane_b32 s30, v0
	global_load_lds_dwordx4 v[4:5], off
	v_lshl_add_u64 v[2:3], v[4:5], 0, s[94:95]
	s_mov_b32 m0, s30
	v_lshrrev_b32_e32 v0, 5, v8
	global_load_lds_dwordx4 v[2:3], off
	v_bfe_u32 v3, v8, 1, 3
	v_bitop3_b32 v0, v0, v3, 1 bitop3:0x6c
	v_lshlrev_b32_e32 v189, 4, v0
	v_bitop3_b32 v0, v9, v3, 2 bitop3:0x36
	v_lshlrev_b32_e32 v190, 4, v0
	v_bitop3_b32 v0, v9, v3, 4 bitop3:0x36
	v_and_b32_e32 v2, 31, v8
	s_waitcnt vmcnt(0)
	v_lshlrev_b32_e32 v191, 4, v0
	v_bitop3_b32 v0, v9, v3, 6 bitop3:0x36
	v_mov_b32_e32 v14, v1
	v_mov_b32_e32 v15, v1
	v_or_b32_e32 v184, v2, v148
	v_lshlrev_b32_e32 v188, 7, v2
	v_lshlrev_b32_e32 v185, 2, v9
	v_lshlrev_b32_e32 v192, 4, v0
	v_mov_b32_e32 v0, v1
	v_mov_b32_e32 v2, v1
	v_mov_b32_e32 v3, v1
	v_mov_b32_e32 v4, v1
	v_mov_b32_e32 v5, v1
	v_mov_b32_e32 v6, v1
	v_mov_b32_e32 v7, v1
	v_mov_b32_e32 v8, v1
	v_mov_b32_e32 v9, v1
	v_mov_b32_e32 v10, v1
	v_mov_b32_e32 v11, v1
	v_mov_b32_e32 v12, v1
	v_mov_b32_e32 v13, v1
	v_mov_b64_e32 v[46:47], v[14:15]
	v_mov_b64_e32 v[62:63], v[14:15]
	v_mov_b64_e32 v[78:79], v[14:15]
	v_mov_b64_e32 v[94:95], v[14:15]
	s_mov_b32 s54, 1
	v_lshl_add_u64 v[160:161], v[156:157], 0, s[28:29]
	s_mov_b32 s55, 0
	v_mov_b32_e32 v186, 0
	v_mov_b64_e32 v[164:165], v[154:155]
	v_mov_b64_e32 v[44:45], v[12:13]
	v_mov_b64_e32 v[42:43], v[10:11]
	v_mov_b64_e32 v[40:41], v[8:9]
	v_mov_b64_e32 v[38:39], v[6:7]
	v_mov_b64_e32 v[36:37], v[4:5]
	v_mov_b64_e32 v[34:35], v[2:3]
	v_mov_b64_e32 v[32:33], v[0:1]
	v_mov_b64_e32 v[60:61], v[12:13]
	v_mov_b64_e32 v[58:59], v[10:11]
	v_mov_b64_e32 v[56:57], v[8:9]
	v_mov_b64_e32 v[54:55], v[6:7]
	v_mov_b64_e32 v[52:53], v[4:5]
	v_mov_b64_e32 v[50:51], v[2:3]
	v_mov_b64_e32 v[48:49], v[0:1]
	v_mov_b64_e32 v[76:77], v[12:13]
	v_mov_b64_e32 v[74:75], v[10:11]
	v_mov_b64_e32 v[72:73], v[8:9]
	v_mov_b64_e32 v[70:71], v[6:7]
	v_mov_b64_e32 v[68:69], v[4:5]
	v_mov_b64_e32 v[66:67], v[2:3]
	v_mov_b64_e32 v[64:65], v[0:1]
	v_mov_b64_e32 v[92:93], v[12:13]
	v_mov_b64_e32 v[90:91], v[10:11]
	v_mov_b64_e32 v[88:89], v[8:9]
	v_mov_b64_e32 v[86:87], v[6:7]
	v_mov_b64_e32 v[84:85], v[4:5]
	v_mov_b64_e32 v[82:83], v[2:3]
	v_mov_b64_e32 v[80:81], v[0:1]
	s_waitcnt vmcnt(0) lgkmcnt(0)
	s_barrier
	s_branch .LBB0_88

; #define MFMA(a, b, c) __builtin_amdgcn_mfma_f32_32x32x16_bf16((a), (b), (c), 0, 0, 0)
; DI float fexp2(float x) { return __builtin_amdgcn_exp2f(x); }
; DI void diff_pass(const bf16_t* __restrict__ qrow  , const bf16_t* __restrict__ kg, const bf16_t* __restrict__ vg,
;                   int nkt, int q0, float negM2, f32x16 (&O)[4], float& lsum, char* lds) {
;     ...
;         if (kt * 64 <= q0 + 31) {
;             f32x16 Sx[2];
;             {
;                 bf16x8 kf[2][4];
; #pragma unroll
;                 for (int kb = 0; kb < 2; ++kb)
; #pragma unroll
;                     for (int ks = 0; ks < 4; ++ks) kf[kb][ks] = *(const bf16x8*)(st + (32 * kb + l31) * 128 + (((2 * ks + h) ^ f) << 4));
;                 __builtin_amdgcn_sched_barrier(0);
; #pragma unroll
;                 for (int ks = 0; ks < 4; ++ks)
; #pragma unroll
;                     for (int kb = 0; kb < 2; ++kb) Sx[kb] = ks == 0 ? MFMA(kf[kb][0], qf[0], minit) : MFMA(kf[kb][ks], qf[ks], Sx[kb]);
;             }
;             if (kt * 64 + 63 > q0) {
; #pragma unroll
;                 for (int kb = 0; kb < 2; ++kb)
; #pragma unroll
;                     for (int i = 0; i < 16; ++i) {
;                         float p = fexp2(Sx[kb][i]);
;                         const int key = kt * 64 + 32 * kb + (i & 3) + 8 * (i >> 2) + 4 * h;
;                         if (key > qpos) p = 0.f;
;                         lsum += p; Sx[kb][i] = p;
;                     }
;             } else {
;                 float l0 = 0.f, l1 = 0.f;
; #pragma unroll
;                 for (int i = 0; i < 16; ++i) { const float p0 = fexp2(Sx[0][i]), p1 = fexp2(Sx[1][i]); l0 += p0; l1 += p1; Sx[0][i] = p0; Sx[1][i] = p1; }
;                 lsum += l0 + l1;
.LBB0_93:
	s_setprio 0
	v_cmp_le_i32_e32 vcc, s35, v171
	s_and_saveexec_b64 s[28:29], vcc
	s_cbranch_execz .LBB0_99
	v_add_u32_e32 v160, v188, v189
	v_add_u32_e32 v159, v188, v190
	v_add_u32_e32 v158, v188, v191
	v_add_u32_e32 v0, v188, v192
	ds_read_b128 v[2:5], v160 offset:24576
	ds_read_b128 v[6:9], v160 offset:28672
	ds_read_b128 v[10:13], v159 offset:24576
	ds_read_b128 v[188:191], v159 offset:28672
	ds_read_b128 v[192:195], v158 offset:24576
	ds_read_b128 v[196:199], v158 offset:28672
	ds_read_b128 v[200:203], v0 offset:24576
	ds_read_b128 v[204:207], v0 offset:28672
	s_waitcnt lgkmcnt(7)
	v_mfma_f32_32x32x16_bf16 v[96:111], v[2:5], v[140:143], v[16:31]
	s_or_b32 s30, s35, 63
	v_cmp_le_i32_e32 vcc, s30, v148
	s_waitcnt lgkmcnt(6)
	v_mfma_f32_32x32x16_bf16 v[112:127], v[6:9], v[140:143], v[16:31]
	s_waitcnt lgkmcnt(5)
	v_mfma_f32_32x32x16_bf16 v[96:111], v[10:13], v[136:139], v[96:111]
	s_waitcnt lgkmcnt(4)
	v_mfma_f32_32x32x16_bf16 v[112:127], v[188:191], v[136:139], v[112:127]
	s_waitcnt lgkmcnt(3)
	v_mfma_f32_32x32x16_bf16 v[96:111], v[192:195], v[132:135], v[96:111]
	s_waitcnt lgkmcnt(2)
	v_mfma_f32_32x32x16_bf16 v[112:127], v[196:199], v[132:135], v[112:127]
	s_waitcnt lgkmcnt(1)
	v_mfma_f32_32x32x16_bf16 v[96:111], v[200:203], v[128:131], v[96:111]
	s_waitcnt lgkmcnt(0)
	v_mfma_f32_32x32x16_bf16 v[112:127], v[204:207], v[128:131], v[112:127]
	s_nop 9
	v_exp_f32_e32 v2, v96
	v_exp_f32_e32 v4, v97
	v_exp_f32_e32 v6, v98
	v_exp_f32_e32 v8, v99
	v_exp_f32_e32 v10, v100
	v_exp_f32_e32 v12, v101
	v_exp_f32_e32 v14, v102
	v_exp_f32_e32 v3, v112
	v_exp_f32_e32 v5, v113
	v_exp_f32_e32 v7, v114
	v_exp_f32_e32 v9, v115
	v_exp_f32_e32 v11, v116
	v_exp_f32_e32 v13, v117
	v_exp_f32_e32 v15, v118
	v_exp_f32_e32 v96, v103
	v_exp_f32_e32 v97, v119
	v_exp_f32_e32 v100, v104
	v_exp_f32_e32 v101, v120
	v_exp_f32_e32 v104, v105
	v_exp_f32_e32 v105, v121
	v_exp_f32_e32 v98, v106
	v_exp_f32_e32 v99, v122
	v_exp_f32_e32 v102, v107
	v_exp_f32_e32 v103, v123
	v_exp_f32_e32 v106, v108
	v_exp_f32_e32 v107, v124
	v_exp_f32_e32 v108, v109
	v_exp_f32_e32 v109, v125
	v_exp_f32_e32 v112, v110
	v_exp_f32_e32 v113, v126
	v_exp_f32_e32 v110, v111
	v_exp_f32_e32 v111, v127
	s_and_saveexec_b64 s[30:31], vcc
	s_xor_b64 s[30:31], exec, s[30:31]
	s_cbranch_execz .LBB0_96
	v_pk_add_f32 v[114:115], v[2:3], 0 op_sel_hi:[1,0]
	s_nop 0
	v_pk_add_f32 v[114:115], v[4:5], v[114:115]
	s_nop 0
	v_pk_add_f32 v[114:115], v[6:7], v[114:115]
	s_nop 0
	v_pk_add_f32 v[114:115], v[8:9], v[114:115]
	s_nop 0
	v_pk_add_f32 v[114:115], v[10:11], v[114:115]
	s_nop 0
	v_pk_add_f32 v[114:115], v[12:13], v[114:115]
	s_nop 0
	v_pk_add_f32 v[114:115], v[14:15], v[114:115]
	s_nop 0
	v_pk_add_f32 v[114:115], v[96:97], v[114:115]
	s_nop 0
	v_pk_add_f32 v[114:115], v[100:101], v[114:115]
	s_nop 0
	v_pk_add_f32 v[114:115], v[104:105], v[114:115]
	s_nop 0
	v_pk_add_f32 v[114:115], v[98:99], v[114:115]
	s_nop 0
	v_pk_add_f32 v[114:115], v[102:103], v[114:115]
	s_nop 0
	v_pk_add_f32 v[114:115], v[106:107], v[114:115]
	s_nop 0
	v_pk_add_f32 v[114:115], v[108:109], v[114:115]
	s_nop 0
	v_pk_add_f32 v[114:115], v[112:113], v[114:115]
	s_nop 0
	v_pk_add_f32 v[114:115], v[110:111], v[114:115]
	s_nop 0
	v_add_f32_e32 v114, v114, v115
	v_add_f32_e32 v114, v186, v114
